# RET sample-unit initial-state loads: all 16 S0 fragment loads issued up front with counted vmcnt waits (were 6 serialized load->wait->MFMA steps)
# speedup vs baseline: 1.0008x; 1.0008x over previous
.LBB0_1046:
	s_and_b64 vcc, exec, s[12:13]
	s_cbranch_vccz .LBB0_1095
	v_ashrrev_i32_e32 v134, 3, v188
	s_movk_i32 s10, 0x48
	v_lshlrev_b32_e32 v0, 3, v188
	v_ashrrev_i32_e32 v132, 4, v188
	v_and_b32_e32 v1, 3, v238
	v_mul_lo_u32 v195, v134, s10
	s_movk_i32 s10, 0x88
	s_cmp_lg_u32 s37, 0
	v_and_b32_e32 v140, 56, v0
	v_and_b32_e32 v138, 0x78, v0
	v_ashrrev_i32_e32 v135, 31, v134
	v_add_u32_e32 v136, 64, v134
	v_ashrrev_i32_e32 v133, 31, v132
	v_mul_lo_u32 v194, v132, s10
	v_mul_u32_u24_e32 v191, 0x110, v177
	v_and_b32_e32 v189, -16, v238
	v_lshrrev_b32_e32 v192, 2, v177
	v_mul_u32_u24_e32 v193, 0x90, v1
	s_cbranch_scc0 .LBB0_1077
	s_add_i32 s10, s84, s34
	v_or_b32_e32 v142, s10, v177
	v_ashrrev_i32_e32 v143, 31, v142
	v_lshlrev_b64 v[0:1], 10, v[142:143]
	v_lshl_add_u64 v[0:1], s[38:39], 0, v[0:1]
	s_lshl_b32 s82, s35, 7
	v_lshl_add_u64 v[0:1], v[0:1], 0, s[82:83]
	v_lshlrev_b64 v[82:83], 1, v[130:131]
	v_lshl_add_u64 v[0:1], v[0:1], 0, v[82:83]
	s_add_i32 s10, s35, 5
	global_load_dwordx4 v[22:25], v[0:1], off
	global_load_dwordx4 v[26:29], v[0:1], off offset:64
	v_cvt_f32_ubyte0_e32 v1, s10
	s_mov_b32 s12, 0x42fc0000
	v_cmp_lt_f32_e32 vcc, s12, v1
	s_lshl_b32 s18, s35, 6
	s_and_b64 s[10:11], vcc, exec
	v_cndmask_b32_e32 v2, 0, v247, vcc
	v_sub_f32_e32 v1, v2, v1
	v_exp_f32_e32 v1, v1
	s_cselect_b32 s10, 0xffffffc0, 0
	v_mov_b32_e32 v3, 0x3e4ccccd
	v_cvt_f32_ubyte0_e32 v0, s35
	v_ldexp_f32 v1, v1, s10
	v_fmamk_f32 v2, v1, 0x3e2aaaab, v3
	v_fmaak_f32 v2, v1, v2, 0x3e800000
	v_fmaak_f32 v2, v1, v2, 0x3eaaaaab
	v_fma_f32 v2, v1, v2, 0.5
	v_fma_f32 v2, v1, v2, 1.0
	v_add_f32_e32 v0, 0x40b00000, v0
	v_mul_f32_e64 v1, v2, -v1
	v_cmp_lt_f32_e32 vcc, s12, v0
	v_mul_f32_e32 v196, 0x3fb8aa3b, v1
	s_and_b64 s[10:11], vcc, exec
	v_cndmask_b32_e32 v1, 0, v247, vcc
	v_sub_f32_e32 v0, v1, v0
	v_exp_f32_e32 v0, v0
	s_cselect_b32 s10, 0xffffffc0, 0
	v_readlane_b32 s11, v255, 14
	s_mov_b32 s13, s83
	v_ldexp_f32 v0, v0, s10
	v_readlane_b32 s10, v255, 34
	v_fmamk_f32 v1, v0, 0x3e2aaaab, v3
	s_add_i32 s10, s10, s69
	v_fmaak_f32 v1, v0, v1, 0x3e800000
	s_lshl_b32 s12, s10, 1
	s_lshl_b32 s10, s35, 13
	v_fmaak_f32 v1, v0, v1, 0x3eaaaaab
	s_add_u32 s10, s11, s10
	v_readlane_b32 s11, v255, 18
	v_fma_f32 v1, v0, v1, 0.5
	s_addc_u32 s11, s11, 0
	s_lshl_b64 s[14:15], s[12:13], 15
	v_fma_f32 v1, v0, v1, 1.0
	s_add_u32 s14, s10, s14
	v_mul_f32_e64 v0, v1, -v0
	v_lshlrev_b32_e32 v8, 7, v177
	s_addc_u32 s15, s11, s15
	v_mul_f32_e32 v197, 0x3fb8aa3b, v0
	v_lshl_add_u64 v[0:1], s[14:15], 0, v[8:9]
	v_lshl_add_u64 v[14:15], v[0:1], 0, v[82:83]
	global_load_dwordx4 v[4:7], v[14:15], off
	global_load_dwordx4 v[0:3], v[14:15], off offset:64
	global_load_dwordx4 v[114:117], v[14:15], off offset:2048
	global_load_dwordx4 v[38:41], v[14:15], off offset:2112
	v_add_co_u32_e32 v216, vcc, 0x1000, v14
	v_addc_co_u32_e32 v217, vcc, 0, v15, vcc
	global_load_dwordx4 v[98:101], v[216:217], off
	global_load_dwordx4 v[90:93], v[216:217], off offset:64
	global_load_dwordx4 v[102:105], v[216:217], off offset:2048
	global_load_dwordx4 v[34:37], v[216:217], off offset:2112
	v_add_co_u32_e32 v218, vcc, 0x8000, v14
	v_addc_co_u32_e32 v219, vcc, 0, v15, vcc
	global_load_dwordx4 v[30:33], v[218:219], off
	global_load_dwordx4 v[224:227], v[218:219], off offset:64
	global_load_dwordx4 v[106:109], v[218:219], off offset:2048
	global_load_dwordx4 v[94:97], v[218:219], off offset:2112
	v_add_co_u32_e32 v220, vcc, 0x9000, v14
	v_addc_co_u32_e32 v221, vcc, 0, v15, vcc
	global_load_dwordx4 v[122:125], v[220:221], off
	global_load_dwordx4 v[118:121], v[220:221], off offset:64
	global_load_dwordx4 v[126:129], v[220:221], off offset:2048
	global_load_dwordx4 v[110:113], v[220:221], off offset:2112
	v_or_b32_e32 v144, s34, v177
	v_add_u32_e32 v10, 1, v144
	v_cvt_f32_u32_e32 v10, v10
	v_or_b32_e32 v46, 0x1000, v8
	v_mov_b32_e32 v47, v9
	v_or_b32_e32 v52, 0x1800, v8
	v_mul_f32_e32 v11, v196, v10
	v_cmp_gt_f32_e32 vcc, s33, v11
	v_mov_b32_e32 v53, v9
	s_or_b32 s12, s12, 1
	v_cndmask_b32_e32 v11, 0, v247, vcc
	v_fmac_f32_e32 v11, v196, v10
	v_exp_f32_e32 v10, v11
	v_cndmask_b32_e32 v11, 0, v248, vcc
	s_lshl_b64 s[12:13], s[12:13], 15
	s_add_u32 s12, s10, s12
	v_ldexp_f32 v16, v10, v11
	s_addc_u32 s13, s11, s13
	v_ashrrev_i32_e32 v84, 1, v238
	v_and_b32_e32 v198, -8, v84
	s_mov_b32 s85, s83
	s_lshl_b64 s[10:11], s[84:85], 10
	s_add_u32 s10, s38, s10
	s_addc_u32 s11, s39, s11
	v_ashrrev_i32_e32 v137, 31, v136
	v_lshlrev_b32_e32 v60, 1, v138
	v_mov_b32_e32 v61, v9
	v_add_lshl_u32 v199, v140, v195, 1
	v_add_u32_e32 v85, 0, v199
	v_add_lshl_u32 v200, v138, v194, 1
	v_bitop3_b32 v139, v84, -8, v84 bitop3:0x3f
	s_mov_b32 s16, 0
	v_readlane_b32 s85, v254, 54
	s_mul_i32 s60, s48, 0x3000
	s_mul_hi_i32 s57, s48, 0x3000
	v_readlane_b32 s56, v251, 4
	v_add_u32_e32 v141, -3, v144
	v_add_u32_e32 v145, -5, v144
	v_add_u32_e32 v170, -4, v144
	v_add_u32_e32 v172, -6, v144
	v_add_u32_e32 v171, 13, v144
	v_add_u32_e32 v174, 14, v144
	v_add_u32_e32 v173, 11, v144
	v_add_u32_e32 v176, 12, v144
	v_add_u32_e32 v175, 9, v144
	v_add_u32_e32 v190, 10, v144
	v_add_u32_e32 v203, s34, v177
	s_waitcnt vmcnt(12)
	v_mfma_f32_16x16x32_bf16 v[10:13], v[4:7], v[22:25], 0
	v_mfma_f32_16x16x32_bf16 v[10:13], v[0:3], v[26:29], v[10:13]
	s_nop 7
	v_pk_fma_f32 v[18:19], v[16:17], v[10:11], 0 op_sel_hi:[0,1,0]
	v_add_u32_e32 v10, 17, v144
	v_cvt_f32_u32_e32 v10, v10
	v_pk_fma_f32 v[20:21], v[16:17], v[12:13], 0 op_sel_hi:[0,1,0]
	v_mul_f32_e32 v11, v196, v10
	v_cmp_gt_f32_e32 vcc, s33, v11
	s_nop 1
	v_cndmask_b32_e32 v11, 0, v247, vcc
	v_fmac_f32_e32 v11, v196, v10
	v_exp_f32_e32 v10, v11
	v_cndmask_b32_e32 v11, 0, v248, vcc
	v_ldexp_f32 v168, v10, v11
	v_mfma_f32_16x16x32_bf16 v[10:13], v[114:117], v[22:25], 0
	v_mfma_f32_16x16x32_bf16 v[10:13], v[38:41], v[26:29], v[10:13]
	s_nop 7
	v_pk_fma_f32 v[42:43], v[16:17], v[10:11], 0 op_sel_hi:[0,1,0]
	v_lshl_add_u64 v[10:11], s[14:15], 0, v[46:47]
	v_lshl_add_u64 v[10:11], v[10:11], 0, v[82:83]
	s_nop 0
	s_nop 0
	v_pk_fma_f32 v[44:45], v[16:17], v[12:13], 0 op_sel_hi:[0,1,0]
	s_waitcnt vmcnt(11)
	v_mfma_f32_16x16x32_bf16 v[10:13], v[98:101], v[22:25], 0
	s_waitcnt vmcnt(10)
	v_mfma_f32_16x16x32_bf16 v[10:13], v[90:93], v[26:29], v[10:13]
	s_nop 7
	v_pk_fma_f32 v[50:51], v[16:17], v[10:11], 0 op_sel_hi:[0,1,0]
	v_lshl_add_u64 v[10:11], s[14:15], 0, v[52:53]
	v_lshl_add_u64 v[10:11], v[10:11], 0, v[82:83]
	s_nop 0
	s_nop 0
	v_pk_fma_f32 v[48:49], v[16:17], v[12:13], 0 op_sel_hi:[0,1,0]
	v_readlane_b32 s14, v255, 57
	s_waitcnt vmcnt(9)
	v_mfma_f32_16x16x32_bf16 v[10:13], v[102:105], v[22:25], 0
	s_waitcnt vmcnt(8)
	v_mfma_f32_16x16x32_bf16 v[10:13], v[34:37], v[26:29], v[10:13]
	s_nop 7
	v_pk_fma_f32 v[54:55], v[16:17], v[10:11], 0 op_sel_hi:[0,1,0]
	v_lshl_add_u64 v[10:11], s[12:13], 0, v[8:9]
	v_lshl_add_u64 v[58:59], v[10:11], 0, v[82:83]
	v_pk_fma_f32 v[56:57], v[16:17], v[12:13], 0 op_sel_hi:[0,1,0]
	s_nop 0
	s_nop 0
	s_nop 0
	s_nop 0
	v_sub_u32_e32 v8, 0x400, v144
	v_cvt_f32_i32_e32 v8, v8
	v_lshlrev_b64 v[58:59], 11, v[132:133]
	v_mul_f32_e32 v10, v197, v8
	v_cmp_gt_f32_e32 vcc, s33, v10
	s_nop 1
	v_cndmask_b32_e32 v10, 0, v247, vcc
	v_fmac_f32_e32 v10, v197, v8
	v_exp_f32_e32 v8, v10
	v_cndmask_b32_e32 v10, 0, v248, vcc
	v_ldexp_f32 v8, v8, v10
	s_waitcnt vmcnt(7)
	v_mfma_f32_16x16x32_bf16 v[10:13], v[30:33], v[22:25], 0
	s_waitcnt vmcnt(6)
	v_mfma_f32_16x16x32_bf16 v[10:13], v[224:227], v[26:29], v[10:13]
	s_nop 7
	v_pk_fma_f32 v[20:21], v[8:9], v[12:13], v[20:21] op_sel_hi:[0,1,1]
	v_pk_fma_f32 v[18:19], v[8:9], v[10:11], v[18:19] op_sel_hi:[0,1,1]
	s_waitcnt vmcnt(5)
	v_mfma_f32_16x16x32_bf16 v[10:13], v[106:109], v[22:25], 0
	s_waitcnt vmcnt(4)
	v_mfma_f32_16x16x32_bf16 v[10:13], v[94:97], v[26:29], v[10:13]
	s_nop 7
	v_pk_fma_f32 v[42:43], v[8:9], v[10:11], v[42:43] op_sel_hi:[0,1,1]
	v_lshl_add_u64 v[10:11], s[12:13], 0, v[46:47]
	v_lshl_add_u64 v[10:11], v[10:11], 0, v[82:83]
	s_nop 0
	s_nop 0
	v_pk_fma_f32 v[44:45], v[8:9], v[12:13], v[44:45] op_sel_hi:[0,1,1]
	s_waitcnt vmcnt(3)
	v_mfma_f32_16x16x32_bf16 v[10:13], v[122:125], v[22:25], 0
	s_waitcnt vmcnt(2)
	v_mfma_f32_16x16x32_bf16 v[10:13], v[118:121], v[26:29], v[10:13]
	s_nop 7
	v_pk_fma_f32 v[46:47], v[8:9], v[10:11], v[50:51] op_sel_hi:[0,1,1]
	v_lshl_add_u64 v[10:11], s[12:13], 0, v[52:53]
	v_lshl_add_u64 v[10:11], v[10:11], 0, v[82:83]
	s_nop 0
	s_nop 0
	v_pk_fma_f32 v[48:49], v[8:9], v[12:13], v[48:49] op_sel_hi:[0,1,1]
	s_add_u32 s12, s10, s82
	s_addc_u32 s13, s11, 0
	s_lshl_b32 s10, s69, 2
	s_or_b32 s10, s10, s35
	s_mov_b32 s11, s83
	s_lshl_b64 s[10:11], s[10:11], 17
	s_add_u32 s14, s14, s10
	s_waitcnt vmcnt(1)
	v_mfma_f32_16x16x32_bf16 v[10:13], v[126:129], v[22:25], 0
	v_readlane_b32 s10, v255, 58
	s_addc_u32 s15, s10, s11
	v_lshl_add_u64 v[58:59], s[14:15], 0, v[58:59]
	s_waitcnt vmcnt(0)
	v_mfma_f32_16x16x32_bf16 v[10:13], v[110:113], v[26:29], v[10:13]
	v_lshl_add_u64 v[162:163], v[58:59], 0, v[60:61]
	s_mov_b64 s[10:11], 0x10000
	v_lshl_add_u64 v[164:165], v[162:163], 0, s[10:11]
	s_mov_b32 s10, 0x10000
	v_add_co_u32_e32 v62, vcc, s10, v162
	s_nop 2
	v_pk_fma_f32 v[12:13], v[8:9], v[12:13], v[56:57] op_sel_hi:[0,1,1]
	v_pk_fma_f32 v[10:11], v[8:9], v[10:11], v[54:55] op_sel_hi:[0,1,1]
	v_cvt_f32_i32_e32 v8, v198
	v_lshlrev_b64 v[54:55], 10, v[136:137]
	v_lshl_add_u64 v[54:55], s[12:13], 0, v[54:55]
	global_load_dwordx4 v[58:61], v[162:163], off
	v_mul_f32_e64 v50, v8, -v196
	v_mul_f32_e32 v8, v197, v8
	v_exp_f32_e32 v148, v8
	v_or_b32_e32 v8, 1, v198
	v_cvt_f32_i32_e32 v8, v8
	v_exp_f32_e32 v146, v50
	v_addc_co_u32_e32 v63, vcc, 0, v163, vcc
	v_mul_f32_e64 v50, v8, -v196
	v_mul_f32_e32 v8, v197, v8
	v_exp_f32_e32 v149, v8
	v_or_b32_e32 v8, 2, v198
	v_cvt_f32_i32_e32 v8, v8
	v_exp_f32_e32 v147, v50
	global_load_dwordx4 v[62:65], v[62:63], off
	s_mov_b32 s10, 0x20000
	v_mul_f32_e64 v50, v8, -v196
	v_mul_f32_e32 v8, v197, v8
	v_exp_f32_e32 v152, v8
	v_or_b32_e32 v8, 3, v198
	v_cvt_f32_i32_e32 v8, v8
	v_exp_f32_e32 v150, v50
	s_add_i32 s14, s34, 16
	v_add_u32_e32 v137, v144, v139
	v_mul_f32_e64 v50, v8, -v196
	v_mul_f32_e32 v8, v197, v8
	v_exp_f32_e32 v153, v8
	v_or_b32_e32 v8, 4, v198
	v_cvt_f32_i32_e32 v8, v8
	v_exp_f32_e32 v151, v50
	s_mov_b32 s15, 0
	v_mul_f32_e64 v50, v8, -v196
	v_mul_f32_e32 v8, v197, v8
	v_exp_f32_e32 v156, v8
	v_or_b32_e32 v8, 5, v198
	v_cvt_f32_i32_e32 v8, v8
	v_exp_f32_e32 v154, v50
	v_mul_f32_e64 v50, v8, -v196
	v_mul_f32_e32 v8, v197, v8
	v_exp_f32_e32 v157, v8
	v_or_b32_e32 v8, 6, v198
	v_cvt_f32_i32_e32 v8, v8
	v_exp_f32_e32 v155, v50
	v_mul_f32_e64 v50, v8, -v196
	v_mul_f32_e32 v8, v197, v8
	v_exp_f32_e32 v160, v8
	v_or_b32_e32 v8, 7, v84
	v_cvt_f32_i32_e32 v8, v8
	v_exp_f32_e32 v158, v50
	v_mul_f32_e64 v50, v8, -v196
	v_exp_f32_e32 v159, v50
	v_mul_f32_e32 v8, v197, v8
	v_lshlrev_b64 v[50:51], 10, v[134:135]
	v_exp_f32_e32 v161, v8
	v_lshl_add_u64 v[50:51], s[12:13], 0, v[50:51]
	v_lshlrev_b32_e32 v8, 1, v140
	v_lshl_add_u64 v[66:67], v[50:51], 0, v[8:9]
	global_load_dwordx4 v[50:53], v[66:67], off offset:512
	v_lshl_add_u64 v[54:55], v[54:55], 0, v[8:9]
	global_load_dwordx4 v[54:57], v[54:55], off offset:512
	v_add_co_u32_e32 v68, vcc, s10, v66
	s_mov_b32 s10, 0x30000
	s_nop 0
	v_addc_co_u32_e32 v69, vcc, 0, v67, vcc
	global_load_dwordx4 v[70:73], v[68:69], off offset:512
	v_add_co_u32_e32 v66, vcc, s10, v66
	v_lshl_add_u64 v[166:167], s[12:13], 0, v[8:9]
	s_nop 0
	v_addc_co_u32_e32 v67, vcc, 0, v67, vcc
	v_or_b32_e32 v8, 16, v144
	global_load_dwordx4 v[74:77], v[66:67], off offset:512
	s_nop 0
	global_load_dwordx4 v[66:69], v[162:163], off offset:256
	global_load_dwordx4 v[78:81], v[164:165], off offset:256
	s_waitcnt vmcnt(5)
	ds_write_b128 v85, v[50:53]
	s_waitcnt vmcnt(4)
	ds_write_b128 v85, v[54:57] offset:9216
	v_add_u32_e32 v85, 0, v200
	v_add_u32_e32 v84, s84, v8
	ds_write_b128 v85, v[58:61] offset:18432
	ds_write_b128 v85, v[62:65] offset:27136
	v_ashrrev_i32_e32 v85, 31, v84
	v_lshlrev_b64 v[84:85], 10, v[84:85]
	v_lshl_add_u64 v[84:85], s[38:39], 0, v[84:85]
	v_lshl_add_u64 v[84:85], v[84:85], 0, s[82:83]
	v_lshl_add_u64 v[86:87], v[84:85], 0, v[82:83]
	global_load_dwordx4 v[82:85], v[86:87], off
	s_nop 0
	global_load_dwordx4 v[86:89], v[86:87], off offset:64
	s_waitcnt vmcnt(1)
	v_mfma_f32_16x16x32_bf16 v[4:7], v[4:7], v[82:85], 0
	v_readlane_b32 s10, v254, 42
	v_add_u32_e32 v139, v8, v139
	s_waitcnt vmcnt(0) lgkmcnt(0)
	v_mfma_f32_16x16x32_bf16 v[0:3], v[0:3], v[86:89], v[4:7]
	v_add3_u32 v201, v191, v189, s10
	s_movk_i32 s10, 0x480
	s_barrier
	s_nop 4
	v_pk_fma_f32 v[4:5], v[168:169], v[0:1], 0 op_sel_hi:[0,1,0]
	v_pk_fma_f32 v[6:7], v[168:169], v[2:3], 0 op_sel_hi:[0,1,0]
	v_mfma_f32_16x16x32_bf16 v[0:3], v[114:117], v[82:85], 0
	v_mfma_f32_16x16x32_bf16 v[0:3], v[38:41], v[86:89], v[0:3]
	s_nop 7
	v_pk_fma_f32 v[38:39], v[168:169], v[0:1], 0 op_sel_hi:[0,1,0]
	v_pk_fma_f32 v[40:41], v[168:169], v[2:3], 0 op_sel_hi:[0,1,0]
	v_mfma_f32_16x16x32_bf16 v[0:3], v[98:101], v[82:85], 0
	v_mfma_f32_16x16x32_bf16 v[0:3], v[90:93], v[86:89], v[0:3]
	s_nop 7
	v_pk_fma_f32 v[90:91], v[168:169], v[0:1], 0 op_sel_hi:[0,1,0]
	v_pk_fma_f32 v[92:93], v[168:169], v[2:3], 0 op_sel_hi:[0,1,0]
	v_mfma_f32_16x16x32_bf16 v[0:3], v[102:105], v[82:85], 0
	v_mfma_f32_16x16x32_bf16 v[0:3], v[34:37], v[86:89], v[0:3]
	s_nop 7
	v_pk_fma_f32 v[98:99], v[168:169], v[0:1], 0 op_sel_hi:[0,1,0]
	v_sub_u32_e32 v0, 0x400, v8
	v_cvt_f32_i32_e32 v0, v0
	v_pk_fma_f32 v[100:101], v[168:169], v[2:3], 0 op_sel_hi:[0,1,0]
	v_add_u32_e32 v168, -2, v144
	v_add_u32_e32 v169, -7, v144
	v_mul_f32_e32 v1, v197, v0
	v_cmp_gt_f32_e32 vcc, s33, v1
	s_nop 1
	v_cndmask_b32_e32 v1, 0, v247, vcc
	v_fmac_f32_e32 v1, v197, v0
	v_exp_f32_e32 v0, v1
	v_cndmask_b32_e32 v1, 0, v248, vcc
	v_ldexp_f32 v102, v0, v1
	v_mfma_f32_16x16x32_bf16 v[0:3], v[30:33], v[82:85], 0
	v_mfma_f32_16x16x32_bf16 v[0:3], v[224:227], v[86:89], v[0:3]
	s_nop 7
	v_pk_fma_f32 v[36:37], v[102:103], v[2:3], v[6:7] op_sel_hi:[0,1,1]
	v_pk_fma_f32 v[34:35], v[102:103], v[0:1], v[4:5] op_sel_hi:[0,1,1]
	v_mfma_f32_16x16x32_bf16 v[0:3], v[106:109], v[82:85], 0
	v_mfma_f32_16x16x32_bf16 v[0:3], v[94:97], v[86:89], v[0:3]
	s_nop 7
	v_pk_fma_f32 v[32:33], v[102:103], v[2:3], v[40:41] op_sel_hi:[0,1,1]
	v_pk_fma_f32 v[30:31], v[102:103], v[0:1], v[38:39] op_sel_hi:[0,1,1]
	v_mfma_f32_16x16x32_bf16 v[0:3], v[122:125], v[82:85], 0
	v_mfma_f32_16x16x32_bf16 v[0:3], v[118:121], v[86:89], v[0:3]
	s_nop 7
	v_pk_fma_f32 v[40:41], v[102:103], v[2:3], v[92:93] op_sel_hi:[0,1,1]
	v_pk_fma_f32 v[38:39], v[102:103], v[0:1], v[90:91] op_sel_hi:[0,1,1]
	v_mfma_f32_16x16x32_bf16 v[0:3], v[126:129], v[82:85], 0
	v_mfma_f32_16x16x32_bf16 v[0:3], v[110:113], v[86:89], v[0:3]
	s_nop 7
	v_pk_fma_f32 v[14:15], v[102:103], v[0:1], v[98:99] op_sel_hi:[0,1,1]
	v_mad_u32_u24 v0, v192, s10, v193
	v_readlane_b32 s10, v254, 27
	v_add3_u32 v202, v0, v189, 0
	v_pk_fma_f32 v[16:17], v[102:103], v[2:3], v[100:101] op_sel_hi:[0,1,1]
	v_sub_u32_e32 v0, s10, v177
	v_subrev_u32_e32 v204, s36, v0
	s_cmp_gt_u32 s15, 5
	s_cbranch_scc1 .LBB0_1050
